# grid barrier: early L1 invalidate plus non-leader workgroups polling the cross-XCC release generation directly
# speedup vs baseline: 1.0091x; 1.0050x over previous
.LBB0_115:
	s_or_b64 exec, exec, s[12:13]
	v_cvt_f32_u32_e32 v4, v2
	s_waitcnt vmcnt(0)
	v_readfirstlane_b32 s6, v3
	v_sub_u32_e32 v3, 0, v2
	v_rcp_iflag_f32_e32 v4, v4
	v_add_u32_e32 v5, s6, v1
	v_mul_f32_e32 v4, 0x4f7ffffe, v4
	v_cvt_u32_f32_e32 v4, v4
	v_mul_lo_u32 v1, v3, v4
	v_mul_hi_u32 v1, v4, v1
	v_add_u32_e32 v1, v4, v1
	v_mul_hi_u32 v1, v5, v1
	v_mul_lo_u32 v3, v1, v2
	v_sub_u32_e32 v3, v5, v3
	v_add_u32_e32 v4, 1, v1
	v_sub_u32_e32 v6, v3, v2
	v_cmp_ge_u32_e32 vcc, v3, v2
	s_nop 1
	v_cndmask_b32_e32 v1, v1, v4, vcc
	v_cndmask_b32_e32 v3, v3, v6, vcc
	v_add_u32_e32 v4, 1, v1
	v_cmp_ge_u32_e32 vcc, v3, v2
	v_add_u32_e32 v3, 1, v5
	s_nop 0
	v_cndmask_b32_e32 v1, v1, v4, vcc
	v_mul_lo_u32 v4, v2, v1
	v_add_u32_e32 v2, v4, v2
	v_cmp_ne_u32_e32 vcc, v3, v2
	s_and_saveexec_b64 s[6:7], vcc
	s_xor_b64 s[12:13], exec, s[6:7]
	s_cbranch_execz .LBB0_129
	v_readlane_b32 s6, v253, 22
	v_readlane_b32 s7, v253, 23
	s_waitcnt lgkmcnt(0)
	s_nop 3
	buffer_inv sc1
	global_load_dword v0, v64, s[6:7] sc1
	s_waitcnt vmcnt(0)
	v_cmp_eq_u32_e32 vcc, v0, v1
	s_and_saveexec_b64 s[16:17], vcc
	s_cbranch_execz .LBB0_128
	s_mov_b32 s6, 1
	s_mov_b64 s[20:21], 0
	s_branch .LBB0_119

.LBB0_1155:
	s_or_b64 exec, exec, s[12:13]
	v_cvt_f32_u32_e32 v4, v2
	s_waitcnt vmcnt(0)
	v_readfirstlane_b32 s6, v3
	v_sub_u32_e32 v3, 0, v2
	v_rcp_iflag_f32_e32 v4, v4
	v_add_u32_e32 v5, s6, v1
	v_mul_f32_e32 v4, 0x4f7ffffe, v4
	v_cvt_u32_f32_e32 v4, v4
	v_mul_lo_u32 v1, v3, v4
	v_mul_hi_u32 v1, v4, v1
	v_add_u32_e32 v1, v4, v1
	v_mul_hi_u32 v1, v5, v1
	v_mul_lo_u32 v3, v1, v2
	v_sub_u32_e32 v3, v5, v3
	v_add_u32_e32 v4, 1, v1
	v_cmp_ge_u32_e32 vcc, v3, v2
	s_nop 1
	v_cndmask_b32_e32 v1, v1, v4, vcc
	v_sub_u32_e32 v4, v3, v2
	v_cndmask_b32_e32 v3, v3, v4, vcc
	v_add_u32_e32 v4, 1, v1
	v_cmp_ge_u32_e32 vcc, v3, v2
	v_add_u32_e32 v3, 1, v5
	s_nop 0
	v_cndmask_b32_e32 v1, v1, v4, vcc
	v_mul_lo_u32 v4, v2, v1
	v_add_u32_e32 v2, v4, v2
	v_cmp_ne_u32_e32 vcc, v3, v2
	s_and_saveexec_b64 s[6:7], vcc
	s_xor_b64 s[12:13], exec, s[6:7]
	s_cbranch_execz .LBB0_1169
	v_readlane_b32 s6, v253, 22
	v_readlane_b32 s7, v253, 23
	s_waitcnt lgkmcnt(0)
	s_nop 3
	buffer_inv sc1
	global_load_dword v0, v64, s[6:7] sc1
	s_waitcnt vmcnt(0)
	v_cmp_eq_u32_e32 vcc, v0, v1
	s_and_saveexec_b64 s[16:17], vcc
	s_cbranch_execz .LBB0_1168
	s_mov_b32 s6, 1
	s_mov_b64 s[20:21], 0
	s_branch .LBB0_1159

.LBB0_1797:
	s_or_b64 exec, exec, s[12:13]
	v_cvt_f32_u32_e32 v4, v2
	s_waitcnt vmcnt(0)
	v_readfirstlane_b32 s2, v3
	v_sub_u32_e32 v3, 0, v2
	v_rcp_iflag_f32_e32 v4, v4
	v_add_u32_e32 v5, s2, v1
	v_mul_f32_e32 v4, 0x4f7ffffe, v4
	v_cvt_u32_f32_e32 v4, v4
	v_mul_lo_u32 v1, v3, v4
	v_mul_hi_u32 v1, v4, v1
	v_add_u32_e32 v1, v4, v1
	v_mul_hi_u32 v1, v5, v1
	v_mul_lo_u32 v3, v1, v2
	v_sub_u32_e32 v3, v5, v3
	v_add_u32_e32 v4, 1, v1
	v_cmp_ge_u32_e32 vcc, v3, v2
	s_nop 1
	v_cndmask_b32_e32 v1, v1, v4, vcc
	v_sub_u32_e32 v4, v3, v2
	v_cndmask_b32_e32 v3, v3, v4, vcc
	v_add_u32_e32 v4, 1, v1
	v_cmp_ge_u32_e32 vcc, v3, v2
	v_add_u32_e32 v3, 1, v5
	s_nop 0
	v_cndmask_b32_e32 v1, v1, v4, vcc
	v_mul_lo_u32 v4, v2, v1
	v_add_u32_e32 v2, v4, v2
	v_cmp_ne_u32_e32 vcc, v3, v2
	s_and_saveexec_b64 s[2:3], vcc
	s_xor_b64 s[12:13], exec, s[2:3]
	s_cbranch_execz .LBB0_1811
	v_readlane_b32 s2, v253, 22
	v_readlane_b32 s3, v253, 23
	s_waitcnt lgkmcnt(0)
	s_nop 3
	buffer_inv sc1
	global_load_dword v0, v64, s[2:3] sc1
	s_waitcnt vmcnt(0)
	v_cmp_eq_u32_e32 vcc, v0, v1
	s_and_saveexec_b64 s[20:21], vcc
	s_cbranch_execz .LBB0_1810
	s_mov_b32 s2, 1
	s_mov_b64 s[28:29], 0
	s_branch .LBB0_1801

.LBB0_1924:
	s_or_b64 exec, exec, s[12:13]
	v_cvt_f32_u32_e32 v4, v2
	s_waitcnt vmcnt(0)
	v_readfirstlane_b32 s2, v3
	v_sub_u32_e32 v3, 0, v2
	v_rcp_iflag_f32_e32 v4, v4
	v_add_u32_e32 v5, s2, v1
	v_mul_f32_e32 v4, 0x4f7ffffe, v4
	v_cvt_u32_f32_e32 v4, v4
	v_mul_lo_u32 v1, v3, v4
	v_mul_hi_u32 v1, v4, v1
	v_add_u32_e32 v1, v4, v1
	v_mul_hi_u32 v1, v5, v1
	v_mul_lo_u32 v3, v1, v2
	v_sub_u32_e32 v3, v5, v3
	v_add_u32_e32 v4, 1, v1
	v_cmp_ge_u32_e32 vcc, v3, v2
	s_nop 1
	v_cndmask_b32_e32 v1, v1, v4, vcc
	v_sub_u32_e32 v4, v3, v2
	v_cndmask_b32_e32 v3, v3, v4, vcc
	v_add_u32_e32 v4, 1, v1
	v_cmp_ge_u32_e32 vcc, v3, v2
	v_add_u32_e32 v3, 1, v5
	s_nop 0
	v_cndmask_b32_e32 v1, v1, v4, vcc
	v_mul_lo_u32 v4, v2, v1
	v_add_u32_e32 v2, v4, v2
	v_cmp_ne_u32_e32 vcc, v3, v2
	s_and_saveexec_b64 s[2:3], vcc
	s_xor_b64 s[12:13], exec, s[2:3]
	s_cbranch_execz .LBB0_1938
	v_readlane_b32 s2, v253, 22
	v_readlane_b32 s3, v253, 23
	s_waitcnt lgkmcnt(0)
	s_nop 3
	buffer_inv sc1
	global_load_dword v0, v64, s[2:3] sc1
	s_waitcnt vmcnt(0)
	v_cmp_eq_u32_e32 vcc, v0, v1
	s_and_saveexec_b64 s[20:21], vcc
	s_cbranch_execz .LBB0_1937
	s_mov_b32 s2, 1
	s_mov_b64 s[42:43], 0
	s_branch .LBB0_1928

.LBB0_2187:
	s_or_b64 exec, exec, s[12:13]
	v_cvt_f32_u32_e32 v4, v2
	s_waitcnt vmcnt(0)
	v_readfirstlane_b32 s2, v3
	v_sub_u32_e32 v3, 0, v2
	v_rcp_iflag_f32_e32 v4, v4
	v_add_u32_e32 v5, s2, v1
	v_mul_f32_e32 v4, 0x4f7ffffe, v4
	v_cvt_u32_f32_e32 v4, v4
	v_mul_lo_u32 v1, v3, v4
	v_mul_hi_u32 v1, v4, v1
	v_add_u32_e32 v1, v4, v1
	v_mul_hi_u32 v1, v5, v1
	v_mul_lo_u32 v3, v1, v2
	v_sub_u32_e32 v3, v5, v3
	v_add_u32_e32 v4, 1, v1
	v_cmp_ge_u32_e32 vcc, v3, v2
	s_nop 1
	v_cndmask_b32_e32 v1, v1, v4, vcc
	v_sub_u32_e32 v4, v3, v2
	v_cndmask_b32_e32 v3, v3, v4, vcc
	v_add_u32_e32 v4, 1, v1
	v_cmp_ge_u32_e32 vcc, v3, v2
	v_add_u32_e32 v3, 1, v5
	s_nop 0
	v_cndmask_b32_e32 v1, v1, v4, vcc
	v_mul_lo_u32 v4, v2, v1
	v_add_u32_e32 v2, v4, v2
	v_cmp_ne_u32_e32 vcc, v3, v2
	s_and_saveexec_b64 s[2:3], vcc
	s_xor_b64 s[12:13], exec, s[2:3]
	s_cbranch_execz .LBB0_2201
	v_readlane_b32 s2, v253, 22
	v_readlane_b32 s3, v253, 23
	s_waitcnt lgkmcnt(0)
	s_nop 3
	buffer_inv sc1
	global_load_dword v0, v64, s[2:3] sc1
	s_waitcnt vmcnt(0)
	v_cmp_eq_u32_e32 vcc, v0, v1
	s_and_saveexec_b64 s[16:17], vcc
	s_cbranch_execz .LBB0_2200
	s_mov_b32 s2, 1
	s_mov_b64 s[20:21], 0
	s_branch .LBB0_2191

.LBB0_2261:
	s_or_b64 exec, exec, s[6:7]
	v_cvt_f32_u32_e32 v4, v2
	s_waitcnt vmcnt(0)
	v_readfirstlane_b32 s6, v3
	v_sub_u32_e32 v3, 0, v2
	v_rcp_iflag_f32_e32 v4, v4
	v_add_u32_e32 v5, s6, v1
	v_mul_f32_e32 v4, 0x4f7ffffe, v4
	v_cvt_u32_f32_e32 v4, v4
	v_mul_lo_u32 v1, v3, v4
	v_mul_hi_u32 v1, v4, v1
	v_add_u32_e32 v1, v4, v1
	v_mul_hi_u32 v1, v5, v1
	v_mul_lo_u32 v3, v1, v2
	v_sub_u32_e32 v3, v5, v3
	v_add_u32_e32 v4, 1, v1
	v_cmp_ge_u32_e32 vcc, v3, v2
	s_nop 1
	v_cndmask_b32_e32 v1, v1, v4, vcc
	v_sub_u32_e32 v4, v3, v2
	v_cndmask_b32_e32 v3, v3, v4, vcc
	v_add_u32_e32 v4, 1, v1
	v_cmp_ge_u32_e32 vcc, v3, v2
	v_add_u32_e32 v3, 1, v5
	s_nop 0
	v_cndmask_b32_e32 v1, v1, v4, vcc
	v_mul_lo_u32 v4, v2, v1
	v_add_u32_e32 v2, v4, v2
	v_cmp_ne_u32_e32 vcc, v3, v2
	s_and_saveexec_b64 s[6:7], vcc
	s_xor_b64 s[6:7], exec, s[6:7]
	s_cbranch_execz .LBB0_2275
	v_readlane_b32 s12, v253, 22
	v_readlane_b32 s13, v253, 23
	s_waitcnt lgkmcnt(0)
	s_nop 3
	buffer_inv sc1
	global_load_dword v0, v64, s[12:13] sc1
	s_waitcnt vmcnt(0)
	v_cmp_eq_u32_e32 vcc, v0, v1
	s_and_saveexec_b64 s[12:13], vcc
	s_cbranch_execz .LBB0_2274
	s_mov_b32 s18, 1
	s_mov_b64 s[16:17], 0
	s_branch .LBB0_2265
